# attention staging-only waves (16-row units): K/V global loads for the next step issued before the barrier into a second register set (2-deep), instead of load-wait-write each step
# speedup vs baseline: 1.0222x; 1.0037x over previous
; #define KLOAD(k0) do { const bf16* kt_ = Kh + (long)(k0) * 512; const bf16* rt_ = Rh + (long)(k0) * 64; ks0 = ld8(kt_ + knoff); ks1 = ld8(kt_ + 64 + knoff); kr0 = ld8(rt_ + kroff); } while (0)
; #define VLOAD(k0) do { const bf16* vt_ = Vh + (long)(k0) * 512; vs0 = ld8(vt_ + kvoff); vs1 = ld8(vt_ + 32 * 512 + kvoff); } while (0)
; #define KWRITE(b) do { *(bf16x8*)(KN_lds + (b) * SHM_KN + kwoff) = ks0; *(bf16x8*)(KN_lds + (b) * SHM_KN + 8192 + kwoff) = ks1; *(bf16x8*)(KR_lds + (b) * SHM_KR + kwoff) = kr0; } while (0)
; #define VWRITE(b) do { *(bf16x8*)(V_lds + (b) * SHM_V + vst0) = vs0; *(bf16x8*)(V_lds + (b) * SHM_V + vst1) = vs1; } while (0)
; #define SWAIT() asm volatile("s_waitcnt vmcnt(0)" ::: "memory")
; __device__ __forceinline__ void attn_unit(const bf16* __restrict__ Qg, const bf16* __restrict__ KNg, const bf16* __restrict__ KRg, const bf16* __restrict__ Vg, bf16* __restrict__ AO, ...
;     ...
;   if (q0 + wid * 32 >= L) {
;     KLOAD(tbeg * KVBLK); VLOAD(tbeg * KVBLK); SWAIT(); KWRITE(0); VWRITE(0); __syncthreads();
;     KLOAD((tbeg + 1) * KVBLK); SWAIT(); KWRITE(1); __syncthreads();
;     for (int j = 1; j + 1 < NT; j += 2) {
;       KLOAD((tbeg + j + 1) * KVBLK); VLOAD((tbeg + j) * KVBLK); SWAIT(); KWRITE(0); VWRITE(1); __syncthreads();
;       const bool more = (j + 2 < NT);
;       if (more) KLOAD((tbeg + j + 2) * KVBLK);
;       VLOAD((tbeg + j + 1) * KVBLK); SWAIT(); if (more) KWRITE(1); VWRITE(0); __syncthreads();
;     }
.LBB0_547:
	s_lshl_b32 s1, s8, 1
	s_and_b32 s9, s1, 0xfffffe00
	s_lshl_b64 s[4:5], s[78:79], 10
	v_readlane_b32 s1, v250, 49
	s_add_u32 s1, s1, s4
	v_readlane_b32 s3, v250, 50
	s_addc_u32 s3, s3, s5
	s_lshl_b32 s0, s0, 1
	s_add_u32 s33, s1, s0
	s_addc_u32 s82, s3, 0
	v_readlane_b32 s1, v250, 45
	s_add_u32 s1, s1, s4
	v_readlane_b32 s3, v250, 46
	s_addc_u32 s3, s3, s5
	s_add_u32 s66, s1, s0
	s_addc_u32 s67, s3, 0
	s_lshl_b64 s[0:1], s[78:79], 7
	v_readlane_b32 s3, v250, 47
	s_add_u32 s0, s3, s0
	v_readlane_b32 s3, v250, 48
	s_addc_u32 s1, s3, s1
	s_lshl_b32 s68, s75, 6
	s_ashr_i32 s69, s68, 31
	s_add_i32 s10, s2, s92
	s_lshl_b64 s[2:3], s[68:69], 10
	s_add_u32 s4, s66, s2
	s_addc_u32 s5, s67, s3
	s_lshl_b64 s[6:7], s[68:69], 7
	v_and_b32_e32 v2, 7, v16
	s_add_u32 s6, s0, s6
	v_lshlrev_b32_e32 v11, 3, v16
	v_lshl_or_b32 v12, s90, 3, v2
	v_and_b32_e32 v3, 56, v16
	s_addc_u32 s7, s1, s7
	v_ashrrev_i32_e32 v10, 4, v16
	v_and_b32_e32 v0, 0x78, v11
	v_lshl_or_b32 v2, v12, 9, v3
	v_lshl_or_b32 v4, v12, 6, v3
	s_add_u32 s2, s33, s2
	v_mov_b32_e32 v3, v1
	v_lshl_or_b32 v0, v10, 9, v0
	s_addc_u32 s3, s82, s3
	v_lshl_add_u64 v[6:7], v[2:3], 1, s[4:5]
	v_mov_b32_e32 v5, v1
	global_load_dwordx4 v[66:69], v[6:7], off
	global_load_dwordx4 v[70:73], v[6:7], off offset:128
	v_lshl_add_u64 v[6:7], v[4:5], 1, s[6:7]
	v_lshl_add_u64 v[8:9], v[0:1], 1, s[2:3]
	global_load_dwordx4 v[74:77], v[6:7], off
	global_load_dwordx4 v[78:81], v[8:9], off
	v_add_co_u32_e32 v6, vcc, 0x8000, v8
	v_bfe_u32 v8, v11, 5, 2
	s_nop 0
	v_addc_co_u32_e32 v7, vcc, 0, v9, vcc
	global_load_dwordx4 v[98:101], v[6:7], off
	v_and_b32_e32 v6, 0xfffff0, v10
	v_lshlrev_b32_e32 v7, 1, v10
	v_and_or_b32 v6, v7, 8, v6
	v_lshrrev_b32_e32 v7, 1, v10
	v_and_b32_e32 v9, 3, v10
	v_add_u32_e32 v10, 32, v10
	v_and_b32_e32 v11, 0xfffff0, v10
	v_lshlrev_b32_e32 v10, 1, v10
	v_and_or_b32 v10, v10, 8, v11
	v_lshrrev_b32_e32 v6, 1, v6
	v_lshrrev_b32_e32 v10, 1, v10
	v_or_b32_e32 v6, v6, v8
	v_and_or_b32 v7, v7, 4, v9
	v_lshlrev_b32_e32 v9, 4, v16
	v_or_b32_e32 v8, v10, v8
	v_lshlrev_b32_e32 v6, 9, v6
	v_lshlrev_b32_e32 v7, 6, v7
	v_and_b32_e32 v9, 48, v9
	v_lshlrev_b32_e32 v8, 9, v8
	v_or3_b32 v6, v6, v7, v9
	v_or3_b32 v7, v8, v7, v9
	v_lshlrev_b32_e32 v8, 7, v185
	v_and_b32_e32 v8, 0x1c00, v8
	v_add_u32_e32 v8, s9, v8
	v_lshlrev_b32_e32 v9, 4, v12
	s_movk_i32 s2, 0x1f0
	v_and_or_b32 v107, v9, s2, v8
	v_add_u32_e32 v197, 0, v107
	s_cmp_lt_i32 s10, s95
	s_mov_b64 s[2:3], -1
	v_add_u32_e32 v198, 0, v6
	v_add_u32_e32 v199, 0, v7
	v_add_u32_e32 v200, 0x10000, v197
	v_lshlrev_b64 v[102:103], 1, v[2:3]
	v_lshlrev_b64 v[104:105], 1, v[4:5]
	v_add_u32_e32 v201, 0x12000, v197
	s_cbranch_scc1 .LBB0_556
	s_add_i32 s2, s68, 64
	s_ashr_i32 s3, s2, 31
	s_lshl_b64 s[4:5], s[2:3], 10
	s_add_u32 s4, s66, s4
	s_addc_u32 s5, s67, s5
	s_lshl_b64 s[2:3], s[2:3], 7
	s_add_u32 s2, s0, s2
	v_lshl_add_u64 v[6:7], s[4:5], 0, v[102:103]
	s_waitcnt vmcnt(0)
	s_waitcnt vmcnt(4)
	ds_write_b128 v197, v[66:69] offset:32768
	s_waitcnt vmcnt(3)
	ds_write_b128 v197, v[70:73] offset:40960
	s_waitcnt vmcnt(2)
	ds_write_b128 v200, v[74:77]
	s_waitcnt vmcnt(1)
	ds_write_b128 v198, v[78:81]
	s_waitcnt vmcnt(0)
	ds_write_b128 v199, v[98:101]
	s_waitcnt lgkmcnt(0)
	s_barrier
	s_addc_u32 s3, s1, s3
	global_load_dwordx4 v[2:5], v[6:7], off
	s_nop 0
	global_load_dwordx4 v[6:9], v[6:7], off offset:128
	v_lshl_add_u64 v[10:11], s[2:3], 0, v[104:105]
	global_load_dwordx4 v[10:13], v[10:11], off
	s_waitcnt vmcnt(0)
	s_mov_b32 s9, 1
	v_lshl_add_u64 v[22:23], s[0:1], 0, v[104:105]
	v_lshl_add_u64 v[24:25], s[66:67], 0, v[102:103]
	s_add_i32 s10, s94, -1
	s_add_i32 s2, s68, 0xc0
	s_waitcnt vmcnt(2)
	ds_write_b128 v197, v[2:5] offset:49152
	s_waitcnt vmcnt(1)
	ds_write_b128 v197, v[6:9] offset:57344
	s_waitcnt vmcnt(0)
	ds_write_b128 v201, v[10:13]
	s_waitcnt lgkmcnt(0)
	s_add_i32 s6, s2, 0xffffff80
	s_sub_i32 s4, s2, 64
	s_ashr_i32 s5, s4, 31
	s_ashr_i32 s7, s6, 31
	s_lshl_b64 s[12:13], s[4:5], 7
	s_lshl_b64 s[14:15], s[4:5], 10
	s_lshl_b64 s[6:7], s[6:7], 10
	s_add_u32 s6, s33, s6
	s_addc_u32 s7, s82, s7
	v_lshl_add_u64 v[46:47], v[24:25], 0, s[14:15]
	v_lshl_add_u64 v[48:49], v[22:23], 0, s[12:13]
	global_load_dwordx4 v[2:5], v[46:47], off
	global_load_dwordx4 v[6:9], v[46:47], off offset:128
	global_load_dwordx4 v[10:13], v[48:49], off
	v_lshl_add_u64 v[46:47], v[0:1], 1, s[6:7]
	v_add_co_u32_e32 v48, vcc, 0x8000, v46
	s_nop 1
	v_addc_co_u32_e32 v49, vcc, 0, v47, vcc
	global_load_dwordx4 v[14:17], v[46:47], off
	global_load_dwordx4 v[18:21], v[48:49], off
	s_barrier
	s_branch .Lst_E
.Lst_E:
	s_add_i32 s9, s9, 2
	s_waitcnt vmcnt(0)
	ds_write_b128 v197, v[2:5] offset:32768
	ds_write_b128 v197, v[6:9] offset:40960
	ds_write_b128 v200, v[10:13]
	ds_write_b128 v198, v[14:17] offset:16384
	ds_write_b128 v199, v[18:21] offset:16384
	s_cmp_lt_u32 s9, s94
	s_cselect_b64 s[6:7], -1, 0
	s_cbranch_scc0 .Lst_noK
	s_ashr_i32 s3, s2, 31
	s_lshl_b64 s[12:13], s[2:3], 10
	s_lshl_b64 s[14:15], s[2:3], 7
	v_lshl_add_u64 v[46:47], v[24:25], 0, s[12:13]
	v_lshl_add_u64 v[48:49], v[22:23], 0, s[14:15]
	global_load_dwordx4 v[26:29], v[46:47], off
	global_load_dwordx4 v[30:33], v[46:47], off offset:128
	global_load_dwordx4 v[34:37], v[48:49], off
.Lst_noK:
	s_sub_i32 s4, s2, 64
	s_ashr_i32 s5, s4, 31
	s_lshl_b64 s[4:5], s[4:5], 10
	s_add_u32 s4, s33, s4
	s_addc_u32 s5, s82, s5
	v_lshl_add_u64 v[46:47], v[0:1], 1, s[4:5]
	v_add_co_u32_e32 v48, vcc, 0x8000, v46
	s_nop 1
	v_addc_co_u32_e32 v49, vcc, 0, v47, vcc
	global_load_dwordx4 v[38:41], v[46:47], off
	global_load_dwordx4 v[42:45], v[48:49], off
	s_waitcnt lgkmcnt(0)
	s_barrier
	s_waitcnt vmcnt(0)
	s_andn2_b64 vcc, exec, s[6:7]
	s_cbranch_vccnz .Lst_O_noKw
	ds_write_b128 v197, v[26:29] offset:49152
	ds_write_b128 v197, v[30:33] offset:57344
	ds_write_b128 v201, v[34:37]
.Lst_O_noKw:
	ds_write_b128 v198, v[38:41]
	ds_write_b128 v199, v[42:45]
	s_addk_i32 s2, 0x80
	s_cmp_ge_u32 s9, s10
	s_cbranch_scc1 .Lst_O_fin
	s_add_i32 s6, s2, 0xffffff80
	s_sub_i32 s4, s2, 64
	s_ashr_i32 s5, s4, 31
	s_ashr_i32 s7, s6, 31
	s_lshl_b64 s[12:13], s[4:5], 7
	s_lshl_b64 s[14:15], s[4:5], 10
	s_lshl_b64 s[6:7], s[6:7], 10
	s_add_u32 s6, s33, s6
	s_addc_u32 s7, s82, s7
	v_lshl_add_u64 v[46:47], v[24:25], 0, s[14:15]
	v_lshl_add_u64 v[48:49], v[22:23], 0, s[12:13]
	global_load_dwordx4 v[2:5], v[46:47], off
	global_load_dwordx4 v[6:9], v[46:47], off offset:128
	global_load_dwordx4 v[10:13], v[48:49], off
	v_lshl_add_u64 v[46:47], v[0:1], 1, s[6:7]
	v_add_co_u32_e32 v48, vcc, 0x8000, v46
	s_nop 1
	v_addc_co_u32_e32 v49, vcc, 0, v47, vcc
	global_load_dwordx4 v[14:17], v[46:47], off
	global_load_dwordx4 v[18:21], v[48:49], off
	s_waitcnt lgkmcnt(0)
	s_barrier
	s_branch .Lst_E
.Lst_O_fin:
	s_waitcnt lgkmcnt(0)
	s_barrier
	s_branch .LBB0_555
